# prep_rows row loop: loop-invariant gain vectors loaded once, rope-table entry fetched with the row's loads (one vmcnt wait per row instead of four)
# speedup vs baseline: 1.0090x; 1.0029x over previous
; __device__ __forceinline__ unsigned cvtpk(float lo, float hi) { typedef __bf16 bf2 __attribute__((ext_vector_type(2))); f32x2 v = {lo, hi}; bf2 b = __builtin_convertvector(v, bf2); return __builtin_bit_cast(unsigned, b); }
; __device__ __forceinline__ bf16_t tobf(float f) { return (bf16_t)(cvtpk(f, 0.f) & 0xffffu); }
; __device__ __forceinline__ void prep_rows(bf16_t* proj, const float* gq, const float* gk, const float* mq, const float* mkv, const float* rope, int gw, int NGW, int lane) {
;     const int j = lane & 15; const bool up = (lane & 16) != 0;
;     for (int row = gw; row < NTOK; row += NGW) {
;         bf16_t* pr = proj + (size_t)row * LDP; const int l = row & (SEQL - 1); const int pos = (lane < 32) ? (l >> 6) : (l & 63);
;         const f32x2 cs = *(const f32x2*)(rope + ((size_t)pos * 16 + j) * 2);
;         float hv[10];
; #pragma unroll
;         for (int hh = 0; hh < 10; ++hh) hv[hh] = bf1(pr[(hh < 8 ? C_BQ + hh * 64 : C_BK + (hh - 8) * 64) + lane]);
;         const float ggq = gq[lane], ggk = gk[lane];
; #pragma unroll
;         for (int hh = 0; hh < 10; ++hh) {
;             const int base = hh < 8 ? C_BQ + hh * 64 : C_BK + (hh - 8) * 64; const float gg = hh < 8 ? ggq : ggk;
;             float v = hv[hh]; const float ss = wave_sum(v * v);
;             v = v * __builtin_amdgcn_rsqf(ss * (1.f / 64) + EPSN) * gg;
;             const float pv = __shfl_xor(v, 16);
;             const float o = up ? (pv * cs[1] + v * cs[0]) : (v * cs[0] - pv * cs[1]);
;             pr[base + lane] = tobf(o);
;         }
;         {
;             const u32x2 w = *(const u32x2*)(pr + C_CQ + 4 * lane); f32x4 v = {bflo(w.x), bfhi(w.x), bflo(w.y), bfhi(w.y)};
;             const float rs = __builtin_amdgcn_rsqf(wave_sum((v[0] * v[0] + v[1] * v[1]) + (v[2] * v[2] + v[3] * v[3])) * (1.f / 256) + EPSN); const f32x4 gg = ((const f32x4*)mq)[lane];
;             u32x2 o; o.x = cvtpk(v[0] * rs * gg[0], v[1] * rs * gg[1]); o.y = cvtpk(v[2] * rs * gg[2], v[3] * rs * gg[3]); *(u32x2*)(pr + C_CQ + 4 * lane) = o;
;         }
;         {
;             const unsigned w = *(const unsigned*)(pr + C_CKV + 2 * lane); const float a = bflo(w), b = bfhi(w);
;             const float rs = __builtin_amdgcn_rsqf(wave_sum(a * a + b * b) * (1.f / 128) + EPSN); const f32x2 gg = ((const f32x2*)mkv)[lane];
.LBB0_260:
	s_cmp_lt_i32 s24, 3
	s_cselect_b64 s[4:5], -1, 0
	s_cmp_gt_i32 s25, 2
	s_cselect_b64 s[6:7], -1, 0
	s_and_b64 s[4:5], s[4:5], s[6:7]
	s_andn2_b64 vcc, exec, s[4:5]
	s_cbranch_vccnz .LBB0_352
	s_mov_b64 s[34:35], s[0:1]
	s_load_dwordx2 s[36:37], s[34:35], 0x118
	v_mov_b32_e32 v30, v1
	s_lshl_b32 s10, s33, 3
	v_readfirstlane_b32 s3, v30
	s_ashr_i32 s27, s3, 6
	v_and_b32_e32 v38, 63, v30
	s_add_i32 s3, s27, s10
	v_and_b32_e32 v31, 16, v30
	s_cmpk_gt_i32 s3, 0x3fff
	v_cmp_gt_u32_e32 vcc, 32, v38
	v_lshlrev_b32_e32 v2, 1, v38
	v_lshlrev_b32_e32 v4, 4, v38
	v_lshlrev_b32_e32 v40, 3, v38
	s_cbranch_scc1 .LBB0_266
	v_mbcnt_lo_u32_b32 v3, -1, 0
	v_mbcnt_hi_u32_b32 v3, -1, v3
	v_and_b32_e32 v5, 64, v3
	v_add_u32_e32 v5, 64, v5
	v_xor_b32_e32 v12, 1, v3
	v_cmp_lt_i32_e64 s[6:7], v12, v5
	s_waitcnt lgkmcnt(0)
	s_add_u32 s8, s36, 0xf800000
	s_addc_u32 s9, s37, 0
	v_cndmask_b32_e64 v12, v3, v12, s[6:7]
	v_lshlrev_b32_e32 v32, 2, v12
	v_xor_b32_e32 v12, 2, v3
	v_cmp_lt_i32_e64 s[6:7], v12, v5
	s_load_dwordx8 s[16:23], s[34:35], 0x60
	v_mov_b32_e32 v7, 0
	v_cndmask_b32_e64 v12, v3, v12, s[6:7]
	v_lshlrev_b32_e32 v33, 2, v12
	v_xor_b32_e32 v12, 4, v3
	v_cmp_lt_i32_e64 s[6:7], v12, v5
	v_and_b32_e32 v22, 30, v2
	v_lshrrev_b32_e32 v16, 4, v38
	v_cndmask_b32_e64 v12, v3, v12, s[6:7]
	v_lshlrev_b32_e32 v34, 2, v12
	v_xor_b32_e32 v12, 8, v3
	v_cmp_lt_i32_e64 s[6:7], v12, v5
	v_lshlrev_b32_e32 v6, 2, v38
	v_mov_b32_e32 v41, v7
	v_cndmask_b32_e64 v12, v3, v12, s[6:7]
	v_lshlrev_b32_e32 v35, 2, v12
	v_xor_b32_e32 v12, 16, v3
	v_cmp_lt_i32_e64 s[6:7], v12, v5
	v_add_u32_e32 v16, v16, v22
	v_mov_b32_e32 v18, 0x1500
	v_cndmask_b32_e64 v12, v3, v12, s[6:7]
	v_lshlrev_b32_e32 v36, 2, v12
	v_xor_b32_e32 v12, 32, v3
	v_cmp_lt_i32_e64 s[6:7], v12, v5
	v_mov_b32_e32 v5, v7
	v_cmp_eq_u32_e64 s[4:5], 0, v31
	v_cndmask_b32_e64 v3, v3, v12, s[6:7]
	s_ashr_i32 s6, s27, 31
	s_ashr_i32 s7, s10, 31
	s_add_u32 s10, s27, s10
	s_addc_u32 s6, s6, s7
	s_mulk_i32 s6, 0x1940
	s_mul_hi_u32 s7, s10, 0x1940
	s_add_i32 s7, s7, s6
	s_mulk_i32 s10, 0x1940
	s_waitcnt lgkmcnt(0)
	v_lshl_add_u64 v[12:13], s[20:21], 0, v[4:5]
	v_and_b32_e32 v5, 31, v30
	s_add_u32 s10, s36, s10
	v_lshl_add_u64 v[8:9], s[16:17], 0, v[6:7]
	v_lshl_add_u64 v[10:11], s[18:19], 0, v[6:7]
	v_lshlrev_b32_e32 v37, 2, v3
	v_mov_b32_e32 v3, v7
	v_lshl_add_u64 v[14:15], s[22:23], 0, v[40:41]
	v_lshl_or_b32 v16, v16, 1, v18
	v_mov_b32_e32 v17, v7
	s_addc_u32 s11, s37, s7
	s_mul_hi_i32 s16, s26, 0x1940
	s_mul_i32 s17, s26, 0x1940
	v_lshl_or_b32 v18, v5, 1, v18
	v_mov_b32_e32 v19, v7
	v_or_b32_e32 v6, 0x1400, v6
	v_or_b32_e32 v20, 0x1200, v40
	v_mov_b32_e32 v21, v7
	v_lshlrev_b32_e32 v5, 2, v22
	s_movk_i32 s18, 0x1000
	v_mov_b32_e32 v39, 0x358637bd
	s_mov_b32 s19, s3
	global_load_dwordx4 v[124:127], v[12:13], off
	global_load_dwordx2 v[128:129], v[14:15], off
	s_branch .LBB0_264

; __device__ __forceinline__ bf16_t tobf(float f) { return (bf16_t)(cvtpk(f, 0.f) & 0xffffu); }
; __device__ __forceinline__ void prep_rows(bf16_t* proj, const float* gq, const float* gk, const float* mq, const float* mkv, const float* rope, int gw, int NGW, int lane) {
;     ...
;         bf16_t* pr = proj + (size_t)row * LDP; const int l = row & (SEQL - 1); const int pos = (lane < 32) ? (l >> 6) : (l & 63);
;         const f32x2 cs = *(const f32x2*)(rope + ((size_t)pos * 16 + j) * 2);
;         float hv[10];
; #pragma unroll
;         for (int hh = 0; hh < 10; ++hh) hv[hh] = bf1(pr[(hh < 8 ? C_BQ + hh * 64 : C_BK + (hh - 8) * 64) + lane]);
;         const float ggq = gq[lane], ggk = gk[lane];
; #pragma unroll
;         for (int hh = 0; hh < 10; ++hh) {
;             const int base = hh < 8 ? C_BQ + hh * 64 : C_BK + (hh - 8) * 64; const float gg = hh < 8 ? ggq : ggk;
;             float v = hv[hh]; const float ss = wave_sum(v * v);
;             v = v * __builtin_amdgcn_rsqf(ss * (1.f / 64) + EPSN) * gg;
;             const float pv = __shfl_xor(v, 16);
;             const float o = up ? (pv * cs[1] + v * cs[0]) : (v * cs[0] - pv * cs[1]);
;             pr[base + lane] = tobf(o);
;         }
;     ...
;             const f32x2 c2 = *(const f32x2*)(rope + ((size_t)l * 16 + j) * 2);
.LBB0_264:
	s_waitcnt lgkmcnt(0)
	v_lshl_add_u64 v[22:23], s[10:11], 0, v[2:3]
	global_load_ushort v43, v[22:23], off offset:3072
	global_load_ushort v48, v[22:23], off offset:3200
	global_load_ushort v49, v[22:23], off offset:3328
	global_load_ushort v50, v[22:23], off offset:3456
	global_load_ushort v51, v[22:23], off offset:3584
	global_load_ushort v52, v[22:23], off offset:3712
	global_load_ushort v53, v[22:23], off offset:3840
	global_load_ushort v54, v[22:23], off offset:3968
	v_add_co_u32_e64 v24, s[6:7], s18, v22
	v_lshl_add_u64 v[26:27], s[10:11], 0, v[20:21]
	s_nop 0
	v_addc_co_u32_e64 v25, s[6:7], 0, v23, s[6:7]
	global_load_ushort v55, v[24:25], off
	global_load_ushort v56, v[24:25], off offset:128
	global_load_dword v42, v[8:9], off
	global_load_dword v41, v[10:11], off
	s_bfe_u32 s6, s19, 0x60006
	s_and_b32 s7, s19, 63
	v_mov_b32_e32 v46, s7
	v_mov_b32_e32 v47, s6
	v_lshl_add_u64 v[44:45], s[10:11], 0, v[18:19]
	v_cndmask_b32_e32 v57, v46, v47, vcc
	v_lshl_add_u64 v[28:29], s[10:11], 0, v[6:7]
	global_load_dwordx2 v[46:47], v[26:27], off
	global_load_dword v58, v[28:29], off
	global_load_ushort v59, v[44:45], off
	v_lshl_or_b32 v44, v57, 7, v5
	global_load_dwordx2 v[44:45], v44, s[8:9]
	s_and_saveexec_b64 s[98:99], vcc
	s_and_b32 s100, s19, 0xfff
	v_lshl_or_b32 v122, s100, 7, v5
	global_load_dwordx2 v[120:121], v122, s[8:9]
	s_or_b64 exec, exec, s[98:99]
	s_waitcnt vmcnt(0)
	v_lshlrev_b32_e32 v43, 16, v43
	v_lshlrev_b32_e32 v48, 16, v48
	v_mul_f32_e32 v57, v43, v43
	v_mul_f32_e32 v60, v48, v48
	ds_bpermute_b32 v57, v32, v57
	ds_bpermute_b32 v60, v32, v60
	v_lshlrev_b32_e32 v49, 16, v49
	v_mul_f32_e32 v61, v49, v49
	ds_bpermute_b32 v61, v32, v61
	s_waitcnt lgkmcnt(2)
	v_fmac_f32_e32 v57, v43, v43
	s_waitcnt lgkmcnt(1)
	v_fmac_f32_e32 v60, v48, v48
	ds_bpermute_b32 v64, v33, v57
	ds_bpermute_b32 v65, v33, v60
	s_waitcnt lgkmcnt(2)
	v_fmac_f32_e32 v61, v49, v49
	ds_bpermute_b32 v66, v33, v61
	v_lshlrev_b32_e32 v50, 16, v50
	s_waitcnt lgkmcnt(2)
	v_add_f32_e32 v57, v57, v64
	s_waitcnt lgkmcnt(1)
	v_add_f32_e32 v60, v60, v65
	ds_bpermute_b32 v64, v34, v57
	ds_bpermute_b32 v65, v34, v60
	v_mul_f32_e32 v62, v50, v50
	s_waitcnt lgkmcnt(2)
	v_add_f32_e32 v61, v61, v66
	ds_bpermute_b32 v62, v32, v62
	s_waitcnt lgkmcnt(2)
	v_add_f32_e32 v57, v57, v64
	s_waitcnt lgkmcnt(1)
	v_add_f32_e32 v60, v60, v65
	ds_bpermute_b32 v64, v35, v57
	ds_bpermute_b32 v66, v34, v61
	ds_bpermute_b32 v65, v35, v60
	s_waitcnt lgkmcnt(3)
	v_fmac_f32_e32 v62, v50, v50
	ds_bpermute_b32 v67, v33, v62
	s_waitcnt lgkmcnt(3)
	v_add_f32_e32 v57, v57, v64
	s_waitcnt lgkmcnt(2)
	v_add_f32_e32 v61, v61, v66
	s_waitcnt lgkmcnt(1)
	v_add_f32_e32 v60, v60, v65
	ds_bpermute_b32 v64, v36, v57
	ds_bpermute_b32 v66, v35, v61
	ds_bpermute_b32 v65, v36, v60
	v_lshlrev_b32_e32 v51, 16, v51
	v_mul_f32_e32 v63, v51, v51
	ds_bpermute_b32 v63, v32, v63
	s_waitcnt lgkmcnt(3)
	v_add_f32_e32 v57, v57, v64
	v_add_f32_e32 v62, v62, v67
	s_waitcnt lgkmcnt(2)
	v_add_f32_e32 v61, v61, v66
	s_waitcnt lgkmcnt(1)
	v_add_f32_e32 v60, v60, v65
	ds_bpermute_b32 v64, v37, v57
	ds_bpermute_b32 v67, v34, v62
	ds_bpermute_b32 v66, v36, v61
	ds_bpermute_b32 v65, v37, v60
	s_waitcnt lgkmcnt(4)
	v_fmac_f32_e32 v63, v51, v51
	ds_bpermute_b32 v68, v33, v63
	s_waitcnt lgkmcnt(4)
	v_add_f32_e32 v57, v57, v64
	s_waitcnt lgkmcnt(3)
	v_add_f32_e32 v62, v62, v67
	s_waitcnt lgkmcnt(2)
	v_add_f32_e32 v61, v61, v66
	s_waitcnt lgkmcnt(1)
	v_add_f32_e32 v60, v60, v65
	v_fmamk_f32 v57, v57, 0x3c800000, v39
	ds_bpermute_b32 v67, v35, v62
	ds_bpermute_b32 v66, v37, v61
	v_fmamk_f32 v60, v60, 0x3c800000, v39
	v_rsq_f32_e32 v57, v57
	v_rsq_f32_e32 v60, v60
	s_waitcnt lgkmcnt(2)
	v_add_f32_e32 v63, v63, v68
	ds_bpermute_b32 v68, v34, v63
	v_mul_f32_e32 v43, v57, v43
	s_waitcnt lgkmcnt(2)
	v_add_f32_e32 v62, v62, v67
	s_waitcnt lgkmcnt(1)
	v_add_f32_e32 v61, v61, v66
	v_mul_f32_e32 v48, v60, v48
	v_mul_f32_e32 v43, v42, v43
	ds_bpermute_b32 v67, v36, v62
	v_fmamk_f32 v61, v61, 0x3c800000, v39
	v_mul_f32_e32 v48, v42, v48
	ds_bpermute_b32 v57, v36, v43
	v_rsq_f32_e32 v61, v61
	ds_bpermute_b32 v60, v36, v48
	s_waitcnt lgkmcnt(3)
	v_add_f32_e32 v63, v63, v68
	ds_bpermute_b32 v68, v35, v63
	s_waitcnt lgkmcnt(3)
	v_add_f32_e32 v62, v62, v67
	v_mul_f32_e32 v49, v61, v49
	s_waitcnt lgkmcnt(2)
	v_mul_f32_e32 v57, v45, v57
	ds_bpermute_b32 v67, v37, v62
	v_mul_f32_e32 v49, v42, v49
	s_waitcnt lgkmcnt(2)
	v_mul_f32_e32 v60, v45, v60
	v_cndmask_b32_e64 v57, v57, -v57, s[4:5]
	ds_bpermute_b32 v61, v36, v49
	v_cndmask_b32_e64 v60, v60, -v60, s[4:5]
	v_fmac_f32_e32 v57, v44, v43
	v_lshlrev_b32_e32 v52, 16, v52
	v_fmac_f32_e32 v60, v44, v48
	v_cvt_pk_bf16_f32 v43, v57, s0
	s_waitcnt lgkmcnt(2)
	v_add_f32_e32 v63, v63, v68
	v_cvt_pk_bf16_f32 v48, v60, s0
	global_store_short v[22:23], v43, off offset:3072
	global_store_short v[22:23], v48, off offset:3200
	v_mul_f32_e32 v43, v52, v52
	ds_bpermute_b32 v68, v36, v63
	ds_bpermute_b32 v43, v32, v43
	s_waitcnt lgkmcnt(3)
	v_add_f32_e32 v62, v62, v67
	v_fmamk_f32 v62, v62, 0x3c800000, v39
	s_waitcnt lgkmcnt(2)
	v_mul_f32_e32 v61, v45, v61
	v_rsq_f32_e32 v62, v62
	v_cndmask_b32_e64 v61, v61, -v61, s[4:5]
	v_fmac_f32_e32 v61, v44, v49
	v_cvt_pk_bf16_f32 v49, v61, s0
	s_waitcnt lgkmcnt(1)
	v_add_f32_e32 v48, v63, v68
	s_waitcnt lgkmcnt(0)
	v_fmac_f32_e32 v43, v52, v52
	global_store_short v[22:23], v49, off offset:3328
	ds_bpermute_b32 v49, v37, v48
	ds_bpermute_b32 v60, v33, v43
	v_mul_f32_e32 v50, v62, v50
	v_mul_f32_e32 v50, v42, v50
	ds_bpermute_b32 v62, v36, v50
	s_waitcnt lgkmcnt(2)
	v_add_f32_e32 v48, v48, v49
	s_waitcnt lgkmcnt(1)
; __device__ __forceinline__ bf16_t tobf(float f) { return (bf16_t)(cvtpk(f, 0.f) & 0xffffu); }
; __device__ __forceinline__ void prep_rows(bf16_t* proj, const float* gq, const float* gk, const float* mq, const float* mkv, const float* rope, int gw, int NGW, int lane) {
;     ...
;         for (int hh = 0; hh < 10; ++hh) {
;             const int base = hh < 8 ? C_BQ + hh * 64 : C_BK + (hh - 8) * 64; const float gg = hh < 8 ? ggq : ggk;
;             float v = hv[hh]; const float ss = wave_sum(v * v);
;             v = v * __builtin_amdgcn_rsqf(ss * (1.f / 64) + EPSN) * gg;
;             const float pv = __shfl_xor(v, 16);
;             const float o = up ? (pv * cs[1] + v * cs[0]) : (v * cs[0] - pv * cs[1]);
;             pr[base + lane] = tobf(o);
;         }
	v_add_f32_e32 v43, v43, v60
	v_fmamk_f32 v48, v48, 0x3c800000, v39
	ds_bpermute_b32 v49, v34, v43
	v_rsq_f32_e32 v48, v48
	s_waitcnt lgkmcnt(1)
	v_mul_f32_e32 v57, v45, v62
	v_cndmask_b32_e64 v57, v57, -v57, s[4:5]
	v_lshlrev_b32_e32 v53, 16, v53
	v_fmac_f32_e32 v57, v44, v50
	v_cvt_pk_bf16_f32 v50, v57, s0
	v_mul_f32_e32 v48, v48, v51
	s_waitcnt lgkmcnt(0)
	v_add_f32_e32 v43, v43, v49
	v_mul_f32_e32 v57, v53, v53
	v_mul_f32_e32 v48, v42, v48
	ds_bpermute_b32 v49, v35, v43
	ds_bpermute_b32 v57, v32, v57
	ds_bpermute_b32 v51, v36, v48
	global_store_short v[22:23], v50, off offset:3456
	v_lshlrev_b32_e32 v54, 16, v54
	s_waitcnt lgkmcnt(2)
	v_add_f32_e32 v43, v43, v49
	s_waitcnt lgkmcnt(1)
	v_fmac_f32_e32 v57, v53, v53
	ds_bpermute_b32 v49, v36, v43
	s_waitcnt lgkmcnt(1)
	v_mul_f32_e32 v50, v45, v51
	ds_bpermute_b32 v51, v33, v57
	v_cndmask_b32_e64 v50, v50, -v50, s[4:5]
	v_fmac_f32_e32 v50, v44, v48
	s_waitcnt lgkmcnt(1)
	v_add_f32_e32 v43, v43, v49
	ds_bpermute_b32 v49, v37, v43
	s_waitcnt lgkmcnt(1)
	v_add_f32_e32 v48, v57, v51
	ds_bpermute_b32 v51, v34, v48
	v_cvt_pk_bf16_f32 v50, v50, s0
	global_store_short v[22:23], v50, off offset:3584
	v_mul_f32_e32 v50, v54, v54
	s_waitcnt lgkmcnt(1)
	v_add_f32_e32 v43, v43, v49
	s_waitcnt lgkmcnt(0)
	v_add_f32_e32 v48, v48, v51
	ds_bpermute_b32 v50, v32, v50
	v_fmamk_f32 v43, v43, 0x3c800000, v39
	ds_bpermute_b32 v49, v35, v48
	v_rsq_f32_e32 v43, v43
	v_lshlrev_b32_e32 v55, 16, v55
	s_waitcnt lgkmcnt(1)
	v_fmac_f32_e32 v50, v54, v54
	v_lshlrev_b32_e32 v56, 16, v56
	v_mul_f32_e32 v43, v43, v52
	s_waitcnt lgkmcnt(0)
	v_add_f32_e32 v48, v48, v49
	ds_bpermute_b32 v52, v33, v50
	ds_bpermute_b32 v49, v36, v48
	v_mul_f32_e32 v43, v42, v43
	ds_bpermute_b32 v51, v36, v43
	s_waitcnt lgkmcnt(2)
	v_add_f32_e32 v50, v50, v52
	s_waitcnt lgkmcnt(1)
	v_add_f32_e32 v48, v48, v49
	ds_bpermute_b32 v52, v34, v50
	ds_bpermute_b32 v49, v37, v48
	s_waitcnt lgkmcnt(2)
	v_mul_f32_e32 v51, v45, v51
	v_cndmask_b32_e64 v51, v51, -v51, s[4:5]
	v_fmac_f32_e32 v51, v44, v43
	s_waitcnt lgkmcnt(1)
	v_add_f32_e32 v43, v50, v52
	s_waitcnt lgkmcnt(0)
	v_add_f32_e32 v48, v48, v49
	ds_bpermute_b32 v49, v35, v43
	v_fmamk_f32 v48, v48, 0x3c800000, v39
	v_rsq_f32_e32 v48, v48
	v_cvt_pk_bf16_f32 v51, v51, s0
	global_store_short v[22:23], v51, off offset:3712
	s_waitcnt lgkmcnt(0)
	v_add_f32_e32 v43, v43, v49
	ds_bpermute_b32 v49, v36, v43
	v_mul_f32_e32 v48, v48, v53
	v_mul_f32_e32 v48, v42, v48
	ds_bpermute_b32 v50, v36, v48
	v_mul_f32_e32 v51, v55, v55
	s_waitcnt lgkmcnt(1)
	v_add_f32_e32 v43, v43, v49
	ds_bpermute_b32 v51, v32, v51
	ds_bpermute_b32 v49, v37, v43
	s_waitcnt lgkmcnt(2)
	v_mul_f32_e32 v50, v45, v50
	v_cndmask_b32_e64 v50, v50, -v50, s[4:5]
	v_fmac_f32_e32 v50, v44, v48
	s_waitcnt lgkmcnt(1)
	v_fmac_f32_e32 v51, v55, v55
	s_waitcnt lgkmcnt(0)
	v_add_f32_e32 v43, v43, v49
	v_mul_f32_e32 v49, v56, v56
	ds_bpermute_b32 v48, v33, v51
	ds_bpermute_b32 v49, v32, v49
	v_fmamk_f32 v43, v43, 0x3c800000, v39
	v_rsq_f32_e32 v43, v43
	v_cvt_pk_bf16_f32 v50, v50, s0
	s_waitcnt lgkmcnt(1)
	v_add_f32_e32 v48, v51, v48
	s_waitcnt lgkmcnt(0)
	v_fmac_f32_e32 v49, v56, v56
	ds_bpermute_b32 v51, v34, v48
	ds_bpermute_b32 v52, v33, v49
	v_mul_f32_e32 v43, v43, v54
	v_mul_f32_e32 v42, v42, v43
	global_store_short v[22:23], v50, off offset:3840
	s_waitcnt lgkmcnt(1)
	v_add_f32_e32 v48, v48, v51
	s_waitcnt lgkmcnt(0)
	v_add_f32_e32 v49, v49, v52
	ds_bpermute_b32 v51, v35, v48
	ds_bpermute_b32 v52, v34, v49
	s_waitcnt lgkmcnt(1)
	v_add_f32_e32 v43, v48, v51
	s_waitcnt lgkmcnt(0)
	v_add_f32_e32 v49, v49, v52
	ds_bpermute_b32 v48, v36, v43
	ds_bpermute_b32 v52, v35, v49
	ds_bpermute_b32 v51, v36, v42
	s_waitcnt lgkmcnt(2)
	v_add_f32_e32 v43, v43, v48
	s_waitcnt lgkmcnt(1)
; __device__ __forceinline__ unsigned cvtpk(float lo, float hi) { typedef __bf16 bf2 __attribute__((ext_vector_type(2))); f32x2 v = {lo, hi}; bf2 b = __builtin_convertvector(v, bf2); return __builtin_bit_cast(unsigned, b); }
; __device__ __forceinline__ bf16_t tobf(float f) { return (bf16_t)(cvtpk(f, 0.f) & 0xffffu); }
; __device__ __forceinline__ void prep_rows(bf16_t* proj, const float* gq, const float* gk, const float* mq, const float* mkv, const float* rope, int gw, int NGW, int lane) {
;     ...
;         for (int hh = 0; hh < 10; ++hh) {
;             const int base = hh < 8 ? C_BQ + hh * 64 : C_BK + (hh - 8) * 64; const float gg = hh < 8 ? ggq : ggk;
;             float v = hv[hh]; const float ss = wave_sum(v * v);
;             v = v * __builtin_amdgcn_rsqf(ss * (1.f / 64) + EPSN) * gg;
;             const float pv = __shfl_xor(v, 16);
;             const float o = up ? (pv * cs[1] + v * cs[0]) : (v * cs[0] - pv * cs[1]);
;             pr[base + lane] = tobf(o);
;         }
;         {
;             const u32x2 w = *(const u32x2*)(pr + C_CQ + 4 * lane); f32x4 v = {bflo(w.x), bfhi(w.x), bflo(w.y), bfhi(w.y)};
;             const float rs = __builtin_amdgcn_rsqf(wave_sum((v[0] * v[0] + v[1] * v[1]) + (v[2] * v[2] + v[3] * v[3])) * (1.f / 256) + EPSN); const f32x4 gg = ((const f32x4*)mq)[lane];
;             u32x2 o; o.x = cvtpk(v[0] * rs * gg[0], v[1] * rs * gg[1]); o.y = cvtpk(v[2] * rs * gg[2], v[3] * rs * gg[3]); *(u32x2*)(pr + C_CQ + 4 * lane) = o;
;         }
;         {
;             const unsigned w = *(const unsigned*)(pr + C_CKV + 2 * lane); const float a = bflo(w), b = bfhi(w);
;             const float rs = __builtin_amdgcn_rsqf(wave_sum(a * a + b * b) * (1.f / 128) + EPSN); const f32x2 gg = ((const f32x2*)mkv)[lane];
;             *(unsigned*)(pr + C_CKV + 2 * lane) = cvtpk(a * rs * gg[0], b * rs * gg[1]);
;         }
;         {
;             const float v = bf1(pr[C_CKR + (lane & 31)]); const float pv = __shfl_xor(v, 16);
;             const f32x2 c2 = *(const f32x2*)(rope + ((size_t)l * 16 + j) * 2);
;             const float o = up ? (pv * c2[1] + v * c2[0]) : (v * c2[0] - pv * c2[1]);
;             if (lane < 32) pr[C_CKR + 2 * j + (lane >> 4)] = tobf(o);
	v_add_f32_e32 v49, v49, v52
	ds_bpermute_b32 v48, v37, v43
	s_waitcnt lgkmcnt(1)
	v_mul_f32_e32 v50, v45, v51
	ds_bpermute_b32 v51, v36, v49
	v_cndmask_b32_e64 v50, v50, -v50, s[4:5]
	v_fmac_f32_e32 v50, v44, v42
	s_waitcnt lgkmcnt(1)
	v_add_f32_e32 v43, v43, v48
	v_fmamk_f32 v43, v43, 0x3c800000, v39
	s_waitcnt lgkmcnt(0)
	v_add_f32_e32 v48, v49, v51
	ds_bpermute_b32 v49, v37, v48
	v_rsq_f32_e32 v43, v43
	s_waitcnt lgkmcnt(0)
	v_add_f32_e32 v48, v48, v49
	v_fmamk_f32 v48, v48, 0x3c800000, v39
	v_mul_f32_e32 v42, v43, v55
	v_rsq_f32_e32 v48, v48
	v_mul_f32_e32 v42, v41, v42
	ds_bpermute_b32 v43, v36, v42
	v_cvt_pk_bf16_f32 v49, v50, s0
	global_store_short v[22:23], v49, off offset:3968
	v_mul_f32_e32 v23, v48, v56
	v_mul_f32_e32 v23, v41, v23
	ds_bpermute_b32 v41, v36, v23
	s_waitcnt lgkmcnt(1)
	v_mul_f32_e32 v22, v45, v43
	v_cndmask_b32_e64 v22, v22, -v22, s[4:5]
	v_fmac_f32_e32 v22, v44, v42
	v_cvt_pk_bf16_f32 v22, v22, s0
	global_store_short v[24:25], v22, off
	s_waitcnt lgkmcnt(0)
	v_mul_f32_e32 v22, v45, v41
	v_cndmask_b32_e64 v22, v22, -v22, s[4:5]
	v_fmac_f32_e32 v22, v44, v23
	v_cvt_pk_bf16_f32 v22, v22, s0
	global_store_short v[24:25], v22, off offset:128
	v_and_b32_e32 v43, 0xffff0000, v47
	v_and_b32_e32 v45, 0xffff0000, v46
	v_lshlrev_b32_e32 v42, 16, v47
	v_lshlrev_b32_e32 v44, 16, v46
	v_mov_b32_e32 v48, v45
	v_mov_b32_e32 v49, v43
	v_mov_b32_e32 v46, v44
	v_mov_b32_e32 v47, v42
	v_pk_mul_f32 v[48:49], v[48:49], v[48:49]
	s_nop 0
	v_pk_fma_f32 v[46:47], v[46:47], v[46:47], v[48:49]
	s_nop 0
	v_add_f32_e32 v41, v46, v47
	ds_bpermute_b32 v46, v32, v41
	s_waitcnt lgkmcnt(0)
	v_add_f32_e32 v41, v41, v46
	ds_bpermute_b32 v46, v33, v41
	s_waitcnt lgkmcnt(0)
	v_add_f32_e32 v41, v41, v46
	ds_bpermute_b32 v46, v34, v41
	s_waitcnt lgkmcnt(0)
	v_add_f32_e32 v41, v41, v46
	ds_bpermute_b32 v46, v35, v41
	s_waitcnt lgkmcnt(0)
	v_add_f32_e32 v41, v41, v46
	ds_bpermute_b32 v46, v36, v41
	s_waitcnt lgkmcnt(0)
	v_add_f32_e32 v41, v41, v46
	ds_bpermute_b32 v46, v37, v41
	s_waitcnt lgkmcnt(0)
	v_add_f32_e32 v41, v41, v46
	v_fmamk_f32 v41, v41, 0x3b800000, v39
	v_rsq_f32_e32 v46, v41
	s_nop 0
	v_pk_mul_f32 v[44:45], v[46:47], v[44:45] op_sel_hi:[0,1]
	v_pk_mul_f32 v[42:43], v[46:47], v[42:43] op_sel_hi:[0,1]
	v_pk_mul_f32 v[22:23], v[124:125], v[44:45]
	v_pk_mul_f32 v[24:25], v[126:127], v[42:43]
	v_cvt_pk_bf16_f32 v22, v22, v23
	v_cvt_pk_bf16_f32 v23, v24, v25
	global_store_dwordx2 v[26:27], v[22:23], off
	v_lshlrev_b32_e32 v26, 16, v58
	v_and_b32_e32 v27, 0xffff0000, v58
	v_pk_mul_f32 v[22:23], v[26:27], v[26:27]
	s_nop 0
	v_add_f32_e32 v22, v22, v23
	ds_bpermute_b32 v23, v32, v22
	s_waitcnt lgkmcnt(0)
	v_add_f32_e32 v22, v22, v23
	ds_bpermute_b32 v23, v33, v22
	s_waitcnt lgkmcnt(0)
	v_add_f32_e32 v22, v22, v23
	ds_bpermute_b32 v23, v34, v22
	s_waitcnt lgkmcnt(0)
	v_add_f32_e32 v22, v22, v23
	ds_bpermute_b32 v23, v35, v22
	s_waitcnt lgkmcnt(0)
	v_add_f32_e32 v22, v22, v23
	ds_bpermute_b32 v23, v36, v22
	s_waitcnt lgkmcnt(0)
	v_add_f32_e32 v22, v22, v23
	ds_bpermute_b32 v23, v37, v22
	s_waitcnt lgkmcnt(0)
	v_add_f32_e32 v22, v22, v23
	v_fmamk_f32 v22, v22, 0x3c000000, v39
	v_rsq_f32_e32 v42, v22
	v_lshlrev_b32_e32 v22, 16, v59
	ds_bpermute_b32 v23, v36, v22
	v_pk_mul_f32 v[26:27], v[42:43], v[26:27] op_sel_hi:[0,1]
	v_pk_mul_f32 v[24:25], v[128:129], v[26:27]
	s_nop 0
	v_cvt_pk_bf16_f32 v24, v24, v25
	global_store_dword v[28:29], v24, off
	s_and_saveexec_b64 s[6:7], vcc
	s_cbranch_execz .LBB0_263
	v_lshl_add_u64 v[26:27], s[10:11], 0, v[16:17]
	s_waitcnt lgkmcnt(0)
	v_mul_f32_e32 v23, v121, v23
	v_cndmask_b32_e64 v23, v23, -v23, s[4:5]
	v_fmac_f32_e32 v23, v120, v22
	v_cvt_pk_bf16_f32 v22, v23, s0
	global_store_short v[26:27], v22, off
	s_branch .LBB0_263

; __device__ __forceinline__ unsigned cvtpk(float lo, float hi) { typedef __bf16 bf2 __attribute__((ext_vector_type(2))); f32x2 v = {lo, hi}; bf2 b = __builtin_convertvector(v, bf2); return __builtin_bit_cast(unsigned, b); }
; __device__ __forceinline__ bf16_t tobf(float f) { return (bf16_t)(cvtpk(f, 0.f) & 0xffffu); }
; __device__ __forceinline__ void prep_rows(bf16_t* proj, const float* gq, const float* gk, const float* mq, const float* mkv, const float* rope, int gw, int NGW, int lane) {
;     const int j = lane & 15; const bool up = (lane & 16) != 0;
;     for (int row = gw; row < NTOK; row += NGW) {
;         bf16_t* pr = proj + (size_t)row * LDP; const int l = row & (SEQL - 1); const int pos = (lane < 32) ? (l >> 6) : (l & 63);
;         const f32x2 cs = *(const f32x2*)(rope + ((size_t)pos * 16 + j) * 2);
;         float hv[10];
; #pragma unroll
;         for (int hh = 0; hh < 10; ++hh) hv[hh] = bf1(pr[(hh < 8 ? C_BQ + hh * 64 : C_BK + (hh - 8) * 64) + lane]);
;         const float ggq = gq[lane], ggk = gk[lane];
; #pragma unroll
;         for (int hh = 0; hh < 10; ++hh) {
;             const int base = hh < 8 ? C_BQ + hh * 64 : C_BK + (hh - 8) * 64; const float gg = hh < 8 ? ggq : ggk;
;             float v = hv[hh]; const float ss = wave_sum(v * v);
;             v = v * __builtin_amdgcn_rsqf(ss * (1.f / 64) + EPSN) * gg;
;             const float pv = __shfl_xor(v, 16);
;             const float o = up ? (pv * cs[1] + v * cs[0]) : (v * cs[0] - pv * cs[1]);
;             pr[base + lane] = tobf(o);
;         }
;         {
;             const u32x2 w = *(const u32x2*)(pr + C_CQ + 4 * lane); f32x4 v = {bflo(w.x), bfhi(w.x), bflo(w.y), bfhi(w.y)};
;             const float rs = __builtin_amdgcn_rsqf(wave_sum((v[0] * v[0] + v[1] * v[1]) + (v[2] * v[2] + v[3] * v[3])) * (1.f / 256) + EPSN); const f32x4 gg = ((const f32x4*)mq)[lane];
;             u32x2 o; o.x = cvtpk(v[0] * rs * gg[0], v[1] * rs * gg[1]); o.y = cvtpk(v[2] * rs * gg[2], v[3] * rs * gg[3]); *(u32x2*)(pr + C_CQ + 4 * lane) = o;
;         }
;         {
;             const unsigned w = *(const unsigned*)(pr + C_CKV + 2 * lane); const float a = bflo(w), b = bfhi(w);
;             const float rs = __builtin_amdgcn_rsqf(wave_sum(a * a + b * b) * (1.f / 128) + EPSN); const f32x2 gg = ((const f32x2*)mkv)[lane];
.LBB0_1688:
	s_cmp_lt_i32 s24, 13
	s_cselect_b64 s[4:5], -1, 0
	s_cmp_gt_i32 s25, 12
	s_cselect_b64 s[6:7], -1, 0
	s_and_b64 s[4:5], s[4:5], s[6:7]
	s_andn2_b64 vcc, exec, s[4:5]
	s_cbranch_vccnz .LBB0_1780
	s_mov_b64 s[34:35], s[0:1]
	s_waitcnt lgkmcnt(0)
	s_load_dwordx2 s[36:37], s[34:35], 0x118
	v_mov_b32_e32 v30, v1
	s_lshl_b32 s10, s33, 3
	v_readfirstlane_b32 s3, v30
	s_ashr_i32 s27, s3, 6
	v_and_b32_e32 v38, 63, v30
	s_add_i32 s3, s27, s10
	v_and_b32_e32 v31, 16, v30
	s_cmpk_gt_i32 s3, 0x3fff
	v_cmp_gt_u32_e32 vcc, 32, v38
	v_lshlrev_b32_e32 v2, 1, v38
	v_lshlrev_b32_e32 v4, 4, v38
	v_lshlrev_b32_e32 v40, 3, v38
	s_cbranch_scc1 .LBB0_1694
	v_mbcnt_lo_u32_b32 v3, -1, 0
	v_mbcnt_hi_u32_b32 v3, -1, v3
	v_and_b32_e32 v5, 64, v3
	v_add_u32_e32 v5, 64, v5
	v_xor_b32_e32 v12, 1, v3
	v_cmp_lt_i32_e64 s[6:7], v12, v5
	s_waitcnt lgkmcnt(0)
	s_add_u32 s8, s36, 0xf800000
	s_addc_u32 s9, s37, 0
	v_cndmask_b32_e64 v12, v3, v12, s[6:7]
	v_lshlrev_b32_e32 v32, 2, v12
	v_xor_b32_e32 v12, 2, v3
	v_cmp_lt_i32_e64 s[6:7], v12, v5
	s_load_dwordx8 s[16:23], s[34:35], 0x60
	v_mov_b32_e32 v7, 0
	v_cndmask_b32_e64 v12, v3, v12, s[6:7]
	v_lshlrev_b32_e32 v33, 2, v12
	v_xor_b32_e32 v12, 4, v3
	v_cmp_lt_i32_e64 s[6:7], v12, v5
	v_and_b32_e32 v22, 30, v2
	v_lshrrev_b32_e32 v16, 4, v38
	v_cndmask_b32_e64 v12, v3, v12, s[6:7]
	v_lshlrev_b32_e32 v34, 2, v12
	v_xor_b32_e32 v12, 8, v3
	v_cmp_lt_i32_e64 s[6:7], v12, v5
	v_lshlrev_b32_e32 v6, 2, v38
	v_mov_b32_e32 v41, v7
	v_cndmask_b32_e64 v12, v3, v12, s[6:7]
	v_lshlrev_b32_e32 v35, 2, v12
	v_xor_b32_e32 v12, 16, v3
	v_cmp_lt_i32_e64 s[6:7], v12, v5
	v_add_u32_e32 v16, v16, v22
	v_mov_b32_e32 v18, 0x1500
	v_cndmask_b32_e64 v12, v3, v12, s[6:7]
	v_lshlrev_b32_e32 v36, 2, v12
	v_xor_b32_e32 v12, 32, v3
	v_cmp_lt_i32_e64 s[6:7], v12, v5
	v_mov_b32_e32 v5, v7
	v_cmp_eq_u32_e64 s[4:5], 0, v31
	v_cndmask_b32_e64 v3, v3, v12, s[6:7]
	s_ashr_i32 s6, s27, 31
	s_ashr_i32 s7, s10, 31
	s_add_u32 s10, s27, s10
	s_addc_u32 s6, s6, s7
	s_mulk_i32 s6, 0x1940
	s_mul_hi_u32 s7, s10, 0x1940
	s_add_i32 s7, s7, s6
	s_mulk_i32 s10, 0x1940
	s_waitcnt lgkmcnt(0)
	v_lshl_add_u64 v[12:13], s[20:21], 0, v[4:5]
	v_and_b32_e32 v5, 31, v30
	s_add_u32 s10, s36, s10
	v_lshl_add_u64 v[8:9], s[16:17], 0, v[6:7]
	v_lshl_add_u64 v[10:11], s[18:19], 0, v[6:7]
	v_lshlrev_b32_e32 v37, 2, v3
	v_mov_b32_e32 v3, v7
	v_lshl_add_u64 v[14:15], s[22:23], 0, v[40:41]
	v_lshl_or_b32 v16, v16, 1, v18
	v_mov_b32_e32 v17, v7
	s_addc_u32 s11, s37, s7
	s_mul_hi_i32 s16, s26, 0x1940
	s_mul_i32 s17, s26, 0x1940
	v_lshl_or_b32 v18, v5, 1, v18
	v_mov_b32_e32 v19, v7
	v_or_b32_e32 v6, 0x1400, v6
	v_or_b32_e32 v20, 0x1200, v40
	v_mov_b32_e32 v21, v7
	v_lshlrev_b32_e32 v5, 2, v22
	s_movk_i32 s18, 0x1000
	v_mov_b32_e32 v39, 0x358637bd
	s_mov_b32 s19, s3
	global_load_dwordx4 v[124:127], v[12:13], off offset:1024
	global_load_dwordx2 v[128:129], v[14:15], off offset:512
	s_branch .LBB0_1692

; __device__ __forceinline__ bf16_t tobf(float f) { return (bf16_t)(cvtpk(f, 0.f) & 0xffffu); }
; __device__ __forceinline__ void prep_rows(bf16_t* proj, const float* gq, const float* gk, const float* mq, const float* mkv, const float* rope, int gw, int NGW, int lane) {
;     ...
;         bf16_t* pr = proj + (size_t)row * LDP; const int l = row & (SEQL - 1); const int pos = (lane < 32) ? (l >> 6) : (l & 63);
;         const f32x2 cs = *(const f32x2*)(rope + ((size_t)pos * 16 + j) * 2);
;         float hv[10];
; #pragma unroll
;         for (int hh = 0; hh < 10; ++hh) hv[hh] = bf1(pr[(hh < 8 ? C_BQ + hh * 64 : C_BK + (hh - 8) * 64) + lane]);
;         const float ggq = gq[lane], ggk = gk[lane];
; #pragma unroll
;         for (int hh = 0; hh < 10; ++hh) {
;             const int base = hh < 8 ? C_BQ + hh * 64 : C_BK + (hh - 8) * 64; const float gg = hh < 8 ? ggq : ggk;
;             float v = hv[hh]; const float ss = wave_sum(v * v);
;             v = v * __builtin_amdgcn_rsqf(ss * (1.f / 64) + EPSN) * gg;
;             const float pv = __shfl_xor(v, 16);
;             const float o = up ? (pv * cs[1] + v * cs[0]) : (v * cs[0] - pv * cs[1]);
;             pr[base + lane] = tobf(o);
;         }
;     ...
;             const f32x2 c2 = *(const f32x2*)(rope + ((size_t)l * 16 + j) * 2);
.LBB0_1692:
	s_waitcnt lgkmcnt(0)
	v_lshl_add_u64 v[22:23], s[10:11], 0, v[2:3]
	global_load_ushort v43, v[22:23], off offset:3072
	global_load_ushort v48, v[22:23], off offset:3200
	global_load_ushort v49, v[22:23], off offset:3328
	global_load_ushort v50, v[22:23], off offset:3456
	global_load_ushort v51, v[22:23], off offset:3584
	global_load_ushort v52, v[22:23], off offset:3712
	global_load_ushort v53, v[22:23], off offset:3840
	global_load_ushort v54, v[22:23], off offset:3968
	v_add_co_u32_e64 v24, s[6:7], s18, v22
	v_lshl_add_u64 v[26:27], s[10:11], 0, v[20:21]
	s_nop 0
	v_addc_co_u32_e64 v25, s[6:7], 0, v23, s[6:7]
	global_load_ushort v55, v[24:25], off
	global_load_ushort v56, v[24:25], off offset:128
	global_load_dword v42, v[8:9], off offset:256
	global_load_dword v41, v[10:11], off offset:256
	s_bfe_u32 s6, s19, 0x60006
	s_and_b32 s7, s19, 63
	v_mov_b32_e32 v46, s7
	v_mov_b32_e32 v47, s6
	v_lshl_add_u64 v[44:45], s[10:11], 0, v[18:19]
	v_cndmask_b32_e32 v57, v46, v47, vcc
	v_lshl_add_u64 v[28:29], s[10:11], 0, v[6:7]
	global_load_dwordx2 v[46:47], v[26:27], off
	global_load_dword v58, v[28:29], off
	global_load_ushort v59, v[44:45], off
	v_lshl_or_b32 v44, v57, 7, v5
	global_load_dwordx2 v[44:45], v44, s[8:9]
	s_and_saveexec_b64 s[98:99], vcc
	s_and_b32 s100, s19, 0xfff
	v_lshl_or_b32 v122, s100, 7, v5
	global_load_dwordx2 v[120:121], v122, s[8:9]
	s_or_b64 exec, exec, s[98:99]
	s_waitcnt vmcnt(0)
	v_lshlrev_b32_e32 v43, 16, v43
	v_lshlrev_b32_e32 v48, 16, v48
	v_mul_f32_e32 v57, v43, v43
	v_mul_f32_e32 v60, v48, v48
	ds_bpermute_b32 v57, v32, v57
	ds_bpermute_b32 v60, v32, v60
	v_lshlrev_b32_e32 v49, 16, v49
	v_mul_f32_e32 v61, v49, v49
	ds_bpermute_b32 v61, v32, v61
	s_waitcnt lgkmcnt(2)
	v_fmac_f32_e32 v57, v43, v43
	s_waitcnt lgkmcnt(1)
	v_fmac_f32_e32 v60, v48, v48
	ds_bpermute_b32 v64, v33, v57
	ds_bpermute_b32 v65, v33, v60
	s_waitcnt lgkmcnt(2)
	v_fmac_f32_e32 v61, v49, v49
	ds_bpermute_b32 v66, v33, v61
	v_lshlrev_b32_e32 v50, 16, v50
	s_waitcnt lgkmcnt(2)
	v_add_f32_e32 v57, v57, v64
	s_waitcnt lgkmcnt(1)
	v_add_f32_e32 v60, v60, v65
	ds_bpermute_b32 v64, v34, v57
	ds_bpermute_b32 v65, v34, v60
	v_mul_f32_e32 v62, v50, v50
	s_waitcnt lgkmcnt(2)
	v_add_f32_e32 v61, v61, v66
	ds_bpermute_b32 v62, v32, v62
	s_waitcnt lgkmcnt(2)
	v_add_f32_e32 v57, v57, v64
	s_waitcnt lgkmcnt(1)
	v_add_f32_e32 v60, v60, v65
	ds_bpermute_b32 v64, v35, v57
	ds_bpermute_b32 v66, v34, v61
	ds_bpermute_b32 v65, v35, v60
	s_waitcnt lgkmcnt(3)
	v_fmac_f32_e32 v62, v50, v50
	ds_bpermute_b32 v67, v33, v62
	s_waitcnt lgkmcnt(3)
	v_add_f32_e32 v57, v57, v64
	s_waitcnt lgkmcnt(2)
	v_add_f32_e32 v61, v61, v66
	s_waitcnt lgkmcnt(1)
	v_add_f32_e32 v60, v60, v65
	ds_bpermute_b32 v64, v36, v57
	ds_bpermute_b32 v66, v35, v61
	ds_bpermute_b32 v65, v36, v60
	v_lshlrev_b32_e32 v51, 16, v51
	v_mul_f32_e32 v63, v51, v51
	ds_bpermute_b32 v63, v32, v63
	s_waitcnt lgkmcnt(3)
	v_add_f32_e32 v57, v57, v64
	v_add_f32_e32 v62, v62, v67
	s_waitcnt lgkmcnt(2)
	v_add_f32_e32 v61, v61, v66
	s_waitcnt lgkmcnt(1)
	v_add_f32_e32 v60, v60, v65
	ds_bpermute_b32 v64, v37, v57
	ds_bpermute_b32 v67, v34, v62
	ds_bpermute_b32 v66, v36, v61
	ds_bpermute_b32 v65, v37, v60
	s_waitcnt lgkmcnt(4)
	v_fmac_f32_e32 v63, v51, v51
	ds_bpermute_b32 v68, v33, v63
	s_waitcnt lgkmcnt(4)
	v_add_f32_e32 v57, v57, v64
	s_waitcnt lgkmcnt(3)
	v_add_f32_e32 v62, v62, v67
	s_waitcnt lgkmcnt(2)
	v_add_f32_e32 v61, v61, v66
	s_waitcnt lgkmcnt(1)
	v_add_f32_e32 v60, v60, v65
	v_fmamk_f32 v57, v57, 0x3c800000, v39
	ds_bpermute_b32 v67, v35, v62
	ds_bpermute_b32 v66, v37, v61
	v_fmamk_f32 v60, v60, 0x3c800000, v39
	v_rsq_f32_e32 v57, v57
	v_rsq_f32_e32 v60, v60
	s_waitcnt lgkmcnt(2)
	v_add_f32_e32 v63, v63, v68
	ds_bpermute_b32 v68, v34, v63
	v_mul_f32_e32 v43, v57, v43
	s_waitcnt lgkmcnt(2)
	v_add_f32_e32 v62, v62, v67
	s_waitcnt lgkmcnt(1)
	v_add_f32_e32 v61, v61, v66
	v_mul_f32_e32 v48, v60, v48
	v_mul_f32_e32 v43, v42, v43
	ds_bpermute_b32 v67, v36, v62
	v_fmamk_f32 v61, v61, 0x3c800000, v39
	v_mul_f32_e32 v48, v42, v48
	ds_bpermute_b32 v57, v36, v43
	v_rsq_f32_e32 v61, v61
	ds_bpermute_b32 v60, v36, v48
	s_waitcnt lgkmcnt(3)
	v_add_f32_e32 v63, v63, v68
	ds_bpermute_b32 v68, v35, v63
	s_waitcnt lgkmcnt(3)
	v_add_f32_e32 v62, v62, v67
	v_mul_f32_e32 v49, v61, v49
	s_waitcnt lgkmcnt(2)
	v_mul_f32_e32 v57, v45, v57
	ds_bpermute_b32 v67, v37, v62
	v_mul_f32_e32 v49, v42, v49
	s_waitcnt lgkmcnt(2)
	v_mul_f32_e32 v60, v45, v60
	v_cndmask_b32_e64 v57, v57, -v57, s[4:5]
	ds_bpermute_b32 v61, v36, v49
	v_cndmask_b32_e64 v60, v60, -v60, s[4:5]
	v_fmac_f32_e32 v57, v44, v43
	v_lshlrev_b32_e32 v52, 16, v52
	v_fmac_f32_e32 v60, v44, v48
	v_cvt_pk_bf16_f32 v43, v57, s0
	s_waitcnt lgkmcnt(2)
	v_add_f32_e32 v63, v63, v68
	v_cvt_pk_bf16_f32 v48, v60, s0
	global_store_short v[22:23], v43, off offset:3072
	global_store_short v[22:23], v48, off offset:3200
	v_mul_f32_e32 v43, v52, v52
	ds_bpermute_b32 v68, v36, v63
	ds_bpermute_b32 v43, v32, v43
	s_waitcnt lgkmcnt(3)
	v_add_f32_e32 v62, v62, v67
	v_fmamk_f32 v62, v62, 0x3c800000, v39
	s_waitcnt lgkmcnt(2)
	v_mul_f32_e32 v61, v45, v61
	v_rsq_f32_e32 v62, v62
	v_cndmask_b32_e64 v61, v61, -v61, s[4:5]
	v_fmac_f32_e32 v61, v44, v49
	v_cvt_pk_bf16_f32 v49, v61, s0
	s_waitcnt lgkmcnt(1)
	v_add_f32_e32 v48, v63, v68
	s_waitcnt lgkmcnt(0)
	v_fmac_f32_e32 v43, v52, v52
	global_store_short v[22:23], v49, off offset:3328
	ds_bpermute_b32 v49, v37, v48
	ds_bpermute_b32 v60, v33, v43
	v_mul_f32_e32 v50, v62, v50
	v_mul_f32_e32 v50, v42, v50
	ds_bpermute_b32 v62, v36, v50
	s_waitcnt lgkmcnt(2)
	v_add_f32_e32 v48, v48, v49
	s_waitcnt lgkmcnt(1)
; __device__ __forceinline__ bf16_t tobf(float f) { return (bf16_t)(cvtpk(f, 0.f) & 0xffffu); }
; __device__ __forceinline__ void prep_rows(bf16_t* proj, const float* gq, const float* gk, const float* mq, const float* mkv, const float* rope, int gw, int NGW, int lane) {
;     ...
;         for (int hh = 0; hh < 10; ++hh) {
;             const int base = hh < 8 ? C_BQ + hh * 64 : C_BK + (hh - 8) * 64; const float gg = hh < 8 ? ggq : ggk;
;             float v = hv[hh]; const float ss = wave_sum(v * v);
;             v = v * __builtin_amdgcn_rsqf(ss * (1.f / 64) + EPSN) * gg;
;             const float pv = __shfl_xor(v, 16);
;             const float o = up ? (pv * cs[1] + v * cs[0]) : (v * cs[0] - pv * cs[1]);
;             pr[base + lane] = tobf(o);
;         }
	v_add_f32_e32 v43, v43, v60
	v_fmamk_f32 v48, v48, 0x3c800000, v39
	ds_bpermute_b32 v49, v34, v43
	v_rsq_f32_e32 v48, v48
	s_waitcnt lgkmcnt(1)
	v_mul_f32_e32 v57, v45, v62
	v_cndmask_b32_e64 v57, v57, -v57, s[4:5]
	v_lshlrev_b32_e32 v53, 16, v53
	v_fmac_f32_e32 v57, v44, v50
	v_cvt_pk_bf16_f32 v50, v57, s0
	v_mul_f32_e32 v48, v48, v51
	s_waitcnt lgkmcnt(0)
	v_add_f32_e32 v43, v43, v49
	v_mul_f32_e32 v57, v53, v53
	v_mul_f32_e32 v48, v42, v48
	ds_bpermute_b32 v49, v35, v43
	ds_bpermute_b32 v57, v32, v57
	ds_bpermute_b32 v51, v36, v48
	global_store_short v[22:23], v50, off offset:3456
	v_lshlrev_b32_e32 v54, 16, v54
	s_waitcnt lgkmcnt(2)
	v_add_f32_e32 v43, v43, v49
	s_waitcnt lgkmcnt(1)
	v_fmac_f32_e32 v57, v53, v53
	ds_bpermute_b32 v49, v36, v43
	s_waitcnt lgkmcnt(1)
	v_mul_f32_e32 v50, v45, v51
	ds_bpermute_b32 v51, v33, v57
	v_cndmask_b32_e64 v50, v50, -v50, s[4:5]
	v_fmac_f32_e32 v50, v44, v48
	s_waitcnt lgkmcnt(1)
	v_add_f32_e32 v43, v43, v49
	ds_bpermute_b32 v49, v37, v43
	s_waitcnt lgkmcnt(1)
	v_add_f32_e32 v48, v57, v51
	ds_bpermute_b32 v51, v34, v48
	v_cvt_pk_bf16_f32 v50, v50, s0
	global_store_short v[22:23], v50, off offset:3584
	v_mul_f32_e32 v50, v54, v54
	s_waitcnt lgkmcnt(1)
	v_add_f32_e32 v43, v43, v49
	s_waitcnt lgkmcnt(0)
	v_add_f32_e32 v48, v48, v51
	ds_bpermute_b32 v50, v32, v50
	v_fmamk_f32 v43, v43, 0x3c800000, v39
	ds_bpermute_b32 v49, v35, v48
	v_rsq_f32_e32 v43, v43
	v_lshlrev_b32_e32 v55, 16, v55
	s_waitcnt lgkmcnt(1)
	v_fmac_f32_e32 v50, v54, v54
	v_lshlrev_b32_e32 v56, 16, v56
	v_mul_f32_e32 v43, v43, v52
	s_waitcnt lgkmcnt(0)
	v_add_f32_e32 v48, v48, v49
	ds_bpermute_b32 v52, v33, v50
	ds_bpermute_b32 v49, v36, v48
	v_mul_f32_e32 v43, v42, v43
	ds_bpermute_b32 v51, v36, v43
	s_waitcnt lgkmcnt(2)
	v_add_f32_e32 v50, v50, v52
	s_waitcnt lgkmcnt(1)
	v_add_f32_e32 v48, v48, v49
	ds_bpermute_b32 v52, v34, v50
	ds_bpermute_b32 v49, v37, v48
	s_waitcnt lgkmcnt(2)
	v_mul_f32_e32 v51, v45, v51
	v_cndmask_b32_e64 v51, v51, -v51, s[4:5]
	v_fmac_f32_e32 v51, v44, v43
	s_waitcnt lgkmcnt(1)
	v_add_f32_e32 v43, v50, v52
	s_waitcnt lgkmcnt(0)
	v_add_f32_e32 v48, v48, v49
	ds_bpermute_b32 v49, v35, v43
	v_fmamk_f32 v48, v48, 0x3c800000, v39
	v_rsq_f32_e32 v48, v48
	v_cvt_pk_bf16_f32 v51, v51, s0
	global_store_short v[22:23], v51, off offset:3712
	s_waitcnt lgkmcnt(0)
	v_add_f32_e32 v43, v43, v49
	ds_bpermute_b32 v49, v36, v43
	v_mul_f32_e32 v48, v48, v53
	v_mul_f32_e32 v48, v42, v48
	ds_bpermute_b32 v50, v36, v48
	v_mul_f32_e32 v51, v55, v55
	s_waitcnt lgkmcnt(1)
	v_add_f32_e32 v43, v43, v49
	ds_bpermute_b32 v51, v32, v51
	ds_bpermute_b32 v49, v37, v43
	s_waitcnt lgkmcnt(2)
	v_mul_f32_e32 v50, v45, v50
	v_cndmask_b32_e64 v50, v50, -v50, s[4:5]
	v_fmac_f32_e32 v50, v44, v48
	s_waitcnt lgkmcnt(1)
	v_fmac_f32_e32 v51, v55, v55
	s_waitcnt lgkmcnt(0)
	v_add_f32_e32 v43, v43, v49
	v_mul_f32_e32 v49, v56, v56
	ds_bpermute_b32 v48, v33, v51
	ds_bpermute_b32 v49, v32, v49
	v_fmamk_f32 v43, v43, 0x3c800000, v39
	v_rsq_f32_e32 v43, v43
	v_cvt_pk_bf16_f32 v50, v50, s0
	s_waitcnt lgkmcnt(1)
	v_add_f32_e32 v48, v51, v48
	s_waitcnt lgkmcnt(0)
	v_fmac_f32_e32 v49, v56, v56
	ds_bpermute_b32 v51, v34, v48
	ds_bpermute_b32 v52, v33, v49
	v_mul_f32_e32 v43, v43, v54
	v_mul_f32_e32 v42, v42, v43
	global_store_short v[22:23], v50, off offset:3840
	s_waitcnt lgkmcnt(1)
	v_add_f32_e32 v48, v48, v51
	s_waitcnt lgkmcnt(0)
	v_add_f32_e32 v49, v49, v52
	ds_bpermute_b32 v51, v35, v48
	ds_bpermute_b32 v52, v34, v49
	s_waitcnt lgkmcnt(1)
	v_add_f32_e32 v43, v48, v51
	s_waitcnt lgkmcnt(0)
	v_add_f32_e32 v49, v49, v52
	ds_bpermute_b32 v48, v36, v43
	ds_bpermute_b32 v52, v35, v49
	ds_bpermute_b32 v51, v36, v42
	s_waitcnt lgkmcnt(2)
	v_add_f32_e32 v43, v43, v48
	s_waitcnt lgkmcnt(1)
; __device__ __forceinline__ unsigned cvtpk(float lo, float hi) { typedef __bf16 bf2 __attribute__((ext_vector_type(2))); f32x2 v = {lo, hi}; bf2 b = __builtin_convertvector(v, bf2); return __builtin_bit_cast(unsigned, b); }
; __device__ __forceinline__ bf16_t tobf(float f) { return (bf16_t)(cvtpk(f, 0.f) & 0xffffu); }
; __device__ __forceinline__ void prep_rows(bf16_t* proj, const float* gq, const float* gk, const float* mq, const float* mkv, const float* rope, int gw, int NGW, int lane) {
;     ...
;         for (int hh = 0; hh < 10; ++hh) {
;             const int base = hh < 8 ? C_BQ + hh * 64 : C_BK + (hh - 8) * 64; const float gg = hh < 8 ? ggq : ggk;
;             float v = hv[hh]; const float ss = wave_sum(v * v);
;             v = v * __builtin_amdgcn_rsqf(ss * (1.f / 64) + EPSN) * gg;
;             const float pv = __shfl_xor(v, 16);
;             const float o = up ? (pv * cs[1] + v * cs[0]) : (v * cs[0] - pv * cs[1]);
;             pr[base + lane] = tobf(o);
;         }
;         {
;             const u32x2 w = *(const u32x2*)(pr + C_CQ + 4 * lane); f32x4 v = {bflo(w.x), bfhi(w.x), bflo(w.y), bfhi(w.y)};
;             const float rs = __builtin_amdgcn_rsqf(wave_sum((v[0] * v[0] + v[1] * v[1]) + (v[2] * v[2] + v[3] * v[3])) * (1.f / 256) + EPSN); const f32x4 gg = ((const f32x4*)mq)[lane];
;             u32x2 o; o.x = cvtpk(v[0] * rs * gg[0], v[1] * rs * gg[1]); o.y = cvtpk(v[2] * rs * gg[2], v[3] * rs * gg[3]); *(u32x2*)(pr + C_CQ + 4 * lane) = o;
;         }
;         {
;             const unsigned w = *(const unsigned*)(pr + C_CKV + 2 * lane); const float a = bflo(w), b = bfhi(w);
;             const float rs = __builtin_amdgcn_rsqf(wave_sum(a * a + b * b) * (1.f / 128) + EPSN); const f32x2 gg = ((const f32x2*)mkv)[lane];
;             *(unsigned*)(pr + C_CKV + 2 * lane) = cvtpk(a * rs * gg[0], b * rs * gg[1]);
;         }
;         {
;             const float v = bf1(pr[C_CKR + (lane & 31)]); const float pv = __shfl_xor(v, 16);
;             const f32x2 c2 = *(const f32x2*)(rope + ((size_t)l * 16 + j) * 2);
;             const float o = up ? (pv * c2[1] + v * c2[0]) : (v * c2[0] - pv * c2[1]);
;             if (lane < 32) pr[C_CKR + 2 * j + (lane >> 4)] = tobf(o);
	v_add_f32_e32 v49, v49, v52
	ds_bpermute_b32 v48, v37, v43
	s_waitcnt lgkmcnt(1)
	v_mul_f32_e32 v50, v45, v51
	ds_bpermute_b32 v51, v36, v49
	v_cndmask_b32_e64 v50, v50, -v50, s[4:5]
	v_fmac_f32_e32 v50, v44, v42
	s_waitcnt lgkmcnt(1)
	v_add_f32_e32 v43, v43, v48
	v_fmamk_f32 v43, v43, 0x3c800000, v39
	s_waitcnt lgkmcnt(0)
	v_add_f32_e32 v48, v49, v51
	ds_bpermute_b32 v49, v37, v48
	v_rsq_f32_e32 v43, v43
	s_waitcnt lgkmcnt(0)
	v_add_f32_e32 v48, v48, v49
	v_fmamk_f32 v48, v48, 0x3c800000, v39
	v_mul_f32_e32 v42, v43, v55
	v_rsq_f32_e32 v48, v48
	v_mul_f32_e32 v42, v41, v42
	ds_bpermute_b32 v43, v36, v42
	v_cvt_pk_bf16_f32 v49, v50, s0
	global_store_short v[22:23], v49, off offset:3968
	v_mul_f32_e32 v23, v48, v56
	v_mul_f32_e32 v23, v41, v23
	ds_bpermute_b32 v41, v36, v23
	s_waitcnt lgkmcnt(1)
	v_mul_f32_e32 v22, v45, v43
	v_cndmask_b32_e64 v22, v22, -v22, s[4:5]
	v_fmac_f32_e32 v22, v44, v42
	v_cvt_pk_bf16_f32 v22, v22, s0
	global_store_short v[24:25], v22, off
	s_waitcnt lgkmcnt(0)
	v_mul_f32_e32 v22, v45, v41
	v_cndmask_b32_e64 v22, v22, -v22, s[4:5]
	v_fmac_f32_e32 v22, v44, v23
	v_cvt_pk_bf16_f32 v22, v22, s0
	global_store_short v[24:25], v22, off offset:128
	v_and_b32_e32 v43, 0xffff0000, v47
	v_and_b32_e32 v45, 0xffff0000, v46
	v_lshlrev_b32_e32 v42, 16, v47
	v_lshlrev_b32_e32 v44, 16, v46
	v_mov_b32_e32 v48, v45
	v_mov_b32_e32 v49, v43
	v_mov_b32_e32 v46, v44
	v_mov_b32_e32 v47, v42
	v_pk_mul_f32 v[48:49], v[48:49], v[48:49]
	s_nop 0
	v_pk_fma_f32 v[46:47], v[46:47], v[46:47], v[48:49]
	s_nop 0
	v_add_f32_e32 v41, v46, v47
	ds_bpermute_b32 v46, v32, v41
	s_waitcnt lgkmcnt(0)
	v_add_f32_e32 v41, v41, v46
	ds_bpermute_b32 v46, v33, v41
	s_waitcnt lgkmcnt(0)
	v_add_f32_e32 v41, v41, v46
	ds_bpermute_b32 v46, v34, v41
	s_waitcnt lgkmcnt(0)
	v_add_f32_e32 v41, v41, v46
	ds_bpermute_b32 v46, v35, v41
	s_waitcnt lgkmcnt(0)
	v_add_f32_e32 v41, v41, v46
	ds_bpermute_b32 v46, v36, v41
	s_waitcnt lgkmcnt(0)
	v_add_f32_e32 v41, v41, v46
	ds_bpermute_b32 v46, v37, v41
	s_waitcnt lgkmcnt(0)
	v_add_f32_e32 v41, v41, v46
	v_fmamk_f32 v41, v41, 0x3b800000, v39
	v_rsq_f32_e32 v46, v41
	s_nop 0
	v_pk_mul_f32 v[44:45], v[46:47], v[44:45] op_sel_hi:[0,1]
	v_pk_mul_f32 v[42:43], v[46:47], v[42:43] op_sel_hi:[0,1]
	v_pk_mul_f32 v[22:23], v[124:125], v[44:45]
	v_pk_mul_f32 v[24:25], v[126:127], v[42:43]
	v_cvt_pk_bf16_f32 v22, v22, v23
	v_cvt_pk_bf16_f32 v23, v24, v25
	global_store_dwordx2 v[26:27], v[22:23], off
	v_lshlrev_b32_e32 v26, 16, v58
	v_and_b32_e32 v27, 0xffff0000, v58
	v_pk_mul_f32 v[22:23], v[26:27], v[26:27]
	s_nop 0
	v_add_f32_e32 v22, v22, v23
	ds_bpermute_b32 v23, v32, v22
	s_waitcnt lgkmcnt(0)
	v_add_f32_e32 v22, v22, v23
	ds_bpermute_b32 v23, v33, v22
	s_waitcnt lgkmcnt(0)
	v_add_f32_e32 v22, v22, v23
	ds_bpermute_b32 v23, v34, v22
	s_waitcnt lgkmcnt(0)
	v_add_f32_e32 v22, v22, v23
	ds_bpermute_b32 v23, v35, v22
	s_waitcnt lgkmcnt(0)
	v_add_f32_e32 v22, v22, v23
	ds_bpermute_b32 v23, v36, v22
	s_waitcnt lgkmcnt(0)
	v_add_f32_e32 v22, v22, v23
	ds_bpermute_b32 v23, v37, v22
	s_waitcnt lgkmcnt(0)
	v_add_f32_e32 v22, v22, v23
	v_fmamk_f32 v22, v22, 0x3c000000, v39
	v_rsq_f32_e32 v42, v22
	v_lshlrev_b32_e32 v22, 16, v59
	ds_bpermute_b32 v23, v36, v22
	v_pk_mul_f32 v[26:27], v[42:43], v[26:27] op_sel_hi:[0,1]
	v_pk_mul_f32 v[24:25], v[128:129], v[26:27]
	s_nop 0
	v_cvt_pk_bf16_f32 v24, v24, v25
	global_store_dword v[28:29], v24, off
	s_and_saveexec_b64 s[6:7], vcc
	s_cbranch_execz .LBB0_1691
	v_lshl_add_u64 v[26:27], s[10:11], 0, v[16:17]
	s_waitcnt lgkmcnt(0)
	v_mul_f32_e32 v23, v121, v23
	v_cndmask_b32_e64 v23, v23, -v23, s[4:5]
	v_fmac_f32_e32 v23, v120, v22
	v_cvt_pk_bf16_f32 v22, v23, s0
	global_store_short v[26:27], v22, off
	s_branch .LBB0_1691
